# P6: bf16 residual tile pre-added into the accumulators at the phase start (loads in the seam shadow) instead of 8 load rounds in the fused epilogue
# baseline (speedup 1.0000x reference)
.LBB0_1353:
	s_and_b64 vcc, exec, s[0:1]
	s_cbranch_vccz .LBB0_1465
	s_and_b64 vcc, exec, s[6:7]
	v_readfirstlane_b32 s38, v156
	s_cbranch_vccnz .LBB0_1465
	s_and_b32 s98, s2, 7
	s_lshl_b32 s98, s98, 3
	s_bfe_u32 s99, s2, 0x30003
	s_add_i32 s98, s98, s99
	s_lshr_b32 s99, s2, 6
	s_lshr_b32 s100, s38, 6
	s_lshr_b32 s101, s100, 2
	s_and_b32 s100, s100, 3
	s_lshl_b32 s98, s98, 8
	s_lshl_b32 s101, s101, 6
	s_add_i32 s98, s98, s101
	s_lshl_b32 s98, s98, 11
	s_lshl_b32 s99, s99, 8
	s_lshl_b32 s100, s100, 6
	s_add_i32 s99, s99, s100
	s_lshl_b32 s99, s99, 1
	s_add_i32 s98, s98, s99
	v_and_b32_e32 v176, 15, v157
	v_lshlrev_b32_e32 v176, 11, v176
	v_lshrrev_b32_e32 v177, 4, v157
	v_lshl_add_u32 v176, v177, 4, v176
	v_add_u32_e32 v176, s98, v176
	global_load_dwordx4 v[190:193], v176, s[42:43]
	global_load_dwordx4 v[194:197], v176, s[42:43] offset:64
	v_add_u32_e32 v177, 0x8000, v176
	global_load_dwordx4 v[198:201], v177, s[42:43]
	global_load_dwordx4 v[202:205], v177, s[42:43] offset:64
	v_add_u32_e32 v177, 0x10000, v176
	global_load_dwordx4 v[206:209], v177, s[42:43]
	global_load_dwordx4 v[210:213], v177, s[42:43] offset:64
	v_add_u32_e32 v177, 0x18000, v176
	global_load_dwordx4 v[214:217], v177, s[42:43]
	global_load_dwordx4 v[218:221], v177, s[42:43] offset:64
	v_add_u32_e32 v177, 0x40000, v176
	global_load_dwordx4 v[222:225], v177, s[42:43]
	global_load_dwordx4 v[226:229], v177, s[42:43] offset:64
	v_add_u32_e32 v177, 0x48000, v176
	global_load_dwordx4 v[230:233], v177, s[42:43]
	global_load_dwordx4 v[234:237], v177, s[42:43] offset:64
	v_add_u32_e32 v177, 0x50000, v176
	global_load_dwordx4 v[238:241], v177, s[42:43]
	global_load_dwordx4 v[242:245], v177, s[42:43] offset:64
	v_add_u32_e32 v177, 0x58000, v176
	global_load_dwordx4 v[246:249], v177, s[42:43]
	global_load_dwordx4 v[250:253], v177, s[42:43] offset:64
	s_ashr_i32 s3, s2, 31
	s_lshr_b32 s0, s3, 29
	s_add_i32 s4, s2, s0
	s_and_b32 s0, s4, -8
	s_sub_i32 s6, s2, s0
	s_cmp_gt_i32 s6, -1
	s_cbranch_scc0 .LBB0_1357
	s_lshl_b32 s5, s6, 5
	s_cbranch_execz .LBB0_1358
	s_branch .LBB0_1359

.LBB0_1361:
	s_mov_b64 s[24:25], 0x80
	v_lshl_add_u64 v[8:9], v[4:5], 0, s[24:25]
	s_add_i32 m0, s35, 0x18000
	s_mov_b64 s[28:29], 0x100080
	s_waitcnt vmcnt(2)
	s_barrier
	global_load_lds_dwordx4 v[8:9], off
	v_lshl_add_u64 v[8:9], v[4:5], 0, s[28:29]
	s_add_i32 m0, s35, 0x1a000
	s_mov_b64 s[36:37], 0x40080
	global_load_lds_dwordx4 v[8:9], off
	v_lshl_add_u64 v[8:9], v[4:5], 0, s[36:37]
	s_add_i32 m0, s35, 0x1c000
	s_mov_b64 s[40:41], 0x140080
	global_load_lds_dwordx4 v[8:9], off
	v_lshl_add_u64 v[4:5], v[4:5], 0, s[40:41]
	s_add_i32 m0, s35, 0x1e000
	v_lshrrev_b32_e32 v142, 4, v157
	global_load_lds_dwordx4 v[4:5], off
	s_lshl_b32 s62, s4, 6
	v_or_b32_e32 v168, s62, v3
	v_xor_b32_e32 v5, v142, v187
	v_bitop3_b32 v7, v142, v187, 4 bitop3:0x36
	s_and_b32 s9, s1, 3
	v_lshlrev_b32_e32 v4, 7, v168
	v_lshlrev_b32_e32 v5, 4, v5
	v_lshlrev_b32_e32 v7, 4, v7
	v_or_b32_e32 v8, v4, v5
	v_or_b32_e32 v9, v4, v7
	v_lshl_or_b32 v4, s9, 12, v172
	s_add_i32 s66, s5, 0x100
	s_mov_b32 s5, 0x14800
	v_or_b32_e32 v144, v4, v7
	s_waitcnt vmcnt(4)
	v_add_u32_e32 v134, v6, v186
	v_mov_b32_e32 v6, v133
	v_mov_b32_e32 v7, v133
	s_add_i32 s67, s5, 0x100
	s_mov_b32 s5, 0x18800
	v_or_b32_e32 v143, v4, v5
	s_mov_b32 s4, 0x18000
	s_mov_b32 s7, 0x1c000
	v_mov_b32_e32 v4, v133
	v_mov_b32_e32 v5, v133
	s_add_i32 s64, s6, 0x100
	s_mov_b32 s6, 0x10800
	v_add_u32_e32 v145, 0x100, v8
	v_add_u32_e32 v146, 0x100, v9
	s_add_i32 s68, s5, 0x100
	s_mov_b32 s5, 0x1c800
	v_mov_b64_e32 v[10:11], v[6:7]
	v_mov_b64_e32 v[22:23], v[6:7]
	v_mov_b64_e32 v[26:27], v[6:7]
	v_mov_b64_e32 v[38:39], v[6:7]
	v_mov_b64_e32 v[42:43], v[6:7]
	v_mov_b64_e32 v[54:55], v[6:7]
	v_mov_b64_e32 v[58:59], v[6:7]
	v_mov_b64_e32 v[14:15], v[6:7]
	v_mov_b64_e32 v[18:19], v[6:7]
	v_mov_b64_e32 v[30:31], v[6:7]
	v_mov_b64_e32 v[34:35], v[6:7]
	v_mov_b64_e32 v[46:47], v[6:7]
	v_mov_b64_e32 v[50:51], v[6:7]
	v_mov_b64_e32 v[62:63], v[6:7]
	v_mov_b64_e32 v[66:67], v[6:7]
	v_mov_b64_e32 v[70:71], v[6:7]
	v_mov_b64_e32 v[74:75], v[6:7]
	v_mov_b64_e32 v[86:87], v[6:7]
	v_mov_b64_e32 v[90:91], v[6:7]
	v_mov_b64_e32 v[102:103], v[6:7]
	v_mov_b64_e32 v[106:107], v[6:7]
	v_mov_b64_e32 v[118:119], v[6:7]
	v_mov_b64_e32 v[122:123], v[6:7]
	v_mov_b64_e32 v[78:79], v[6:7]
	v_mov_b64_e32 v[82:83], v[6:7]
	v_mov_b64_e32 v[94:95], v[6:7]
	v_mov_b64_e32 v[98:99], v[6:7]
	v_mov_b64_e32 v[110:111], v[6:7]
	v_mov_b64_e32 v[114:115], v[6:7]
	v_mov_b64_e32 v[126:127], v[6:7]
	v_mov_b64_e32 v[130:131], v[6:7]
	s_sext_i32_i8 s0, s0
	v_mov_b32_e32 v135, v133
	s_mov_b32 s63, 0
	v_mov_b64_e32 v[136:137], 0x100
	v_mov_b64_e32 v[138:139], 0xff
	s_add_i32 s65, s6, 0x100
	s_mov_b64 s[44:45], 0x80080
	s_mov_b64 s[46:47], 0x180080
	s_add_i32 s69, s5, 0x100
	s_add_i32 s70, s4, 0x100
	s_add_i32 s71, s7, 0x100
	v_mov_b64_e32 v[8:9], v[4:5]
	v_mov_b64_e32 v[20:21], v[4:5]
	v_mov_b64_e32 v[24:25], v[4:5]
	v_mov_b64_e32 v[36:37], v[4:5]
	v_mov_b64_e32 v[40:41], v[4:5]
	v_mov_b64_e32 v[52:53], v[4:5]
	v_mov_b64_e32 v[56:57], v[4:5]
	v_mov_b64_e32 v[12:13], v[4:5]
	v_mov_b64_e32 v[16:17], v[4:5]
	v_mov_b64_e32 v[28:29], v[4:5]
	v_mov_b64_e32 v[32:33], v[4:5]
	v_mov_b64_e32 v[44:45], v[4:5]
	v_mov_b64_e32 v[48:49], v[4:5]
	v_mov_b64_e32 v[60:61], v[4:5]
	v_mov_b64_e32 v[64:65], v[4:5]
	v_mov_b64_e32 v[68:69], v[4:5]
	v_mov_b64_e32 v[72:73], v[4:5]
	v_mov_b64_e32 v[84:85], v[4:5]
	v_mov_b64_e32 v[88:89], v[4:5]
	v_mov_b64_e32 v[100:101], v[4:5]
	v_mov_b64_e32 v[104:105], v[4:5]
	v_mov_b64_e32 v[116:117], v[4:5]
	v_mov_b64_e32 v[120:121], v[4:5]
	v_mov_b64_e32 v[76:77], v[4:5]
	v_mov_b64_e32 v[80:81], v[4:5]
	v_mov_b64_e32 v[92:93], v[4:5]
	v_mov_b64_e32 v[96:97], v[4:5]
	v_mov_b64_e32 v[108:109], v[4:5]
	v_mov_b64_e32 v[112:113], v[4:5]
	v_mov_b64_e32 v[124:125], v[4:5]
	v_mov_b64_e32 v[128:129], v[4:5]
	s_waitcnt vmcnt(4)
	v_lshlrev_b32_e32 v128, 16, v190
	v_and_b32_e32 v129, 0xffff0000, v190
	v_lshlrev_b32_e32 v130, 16, v191
	v_and_b32_e32 v131, 0xffff0000, v191
	v_lshlrev_b32_e32 v124, 16, v192
	v_and_b32_e32 v125, 0xffff0000, v192
	v_lshlrev_b32_e32 v126, 16, v193
	v_and_b32_e32 v127, 0xffff0000, v193
	v_lshlrev_b32_e32 v120, 16, v194
	v_and_b32_e32 v121, 0xffff0000, v194
	v_lshlrev_b32_e32 v122, 16, v195
	v_and_b32_e32 v123, 0xffff0000, v195
	v_lshlrev_b32_e32 v116, 16, v196
	v_and_b32_e32 v117, 0xffff0000, v196
	v_lshlrev_b32_e32 v118, 16, v197
	v_and_b32_e32 v119, 0xffff0000, v197
	v_lshlrev_b32_e32 v112, 16, v198
	v_and_b32_e32 v113, 0xffff0000, v198
	v_lshlrev_b32_e32 v114, 16, v199
	v_and_b32_e32 v115, 0xffff0000, v199
	v_lshlrev_b32_e32 v108, 16, v200
	v_and_b32_e32 v109, 0xffff0000, v200
	v_lshlrev_b32_e32 v110, 16, v201
	v_and_b32_e32 v111, 0xffff0000, v201
	v_lshlrev_b32_e32 v104, 16, v202
	v_and_b32_e32 v105, 0xffff0000, v202
	v_lshlrev_b32_e32 v106, 16, v203
	v_and_b32_e32 v107, 0xffff0000, v203
	v_lshlrev_b32_e32 v100, 16, v204
	v_and_b32_e32 v101, 0xffff0000, v204
	v_lshlrev_b32_e32 v102, 16, v205
	v_and_b32_e32 v103, 0xffff0000, v205
	v_lshlrev_b32_e32 v96, 16, v206
	v_and_b32_e32 v97, 0xffff0000, v206
	v_lshlrev_b32_e32 v98, 16, v207
	v_and_b32_e32 v99, 0xffff0000, v207
	v_lshlrev_b32_e32 v92, 16, v208
	v_and_b32_e32 v93, 0xffff0000, v208
	v_lshlrev_b32_e32 v94, 16, v209
	v_and_b32_e32 v95, 0xffff0000, v209
	v_lshlrev_b32_e32 v88, 16, v210
	v_and_b32_e32 v89, 0xffff0000, v210
	v_lshlrev_b32_e32 v90, 16, v211
	v_and_b32_e32 v91, 0xffff0000, v211
	v_lshlrev_b32_e32 v84, 16, v212
	v_and_b32_e32 v85, 0xffff0000, v212
	v_lshlrev_b32_e32 v86, 16, v213
	v_and_b32_e32 v87, 0xffff0000, v213
	v_lshlrev_b32_e32 v80, 16, v214
	v_and_b32_e32 v81, 0xffff0000, v214
	v_lshlrev_b32_e32 v82, 16, v215
	v_and_b32_e32 v83, 0xffff0000, v215
	v_lshlrev_b32_e32 v76, 16, v216
	v_and_b32_e32 v77, 0xffff0000, v216
	v_lshlrev_b32_e32 v78, 16, v217
	v_and_b32_e32 v79, 0xffff0000, v217
	v_lshlrev_b32_e32 v72, 16, v218
	v_and_b32_e32 v73, 0xffff0000, v218
	v_lshlrev_b32_e32 v74, 16, v219
	v_and_b32_e32 v75, 0xffff0000, v219
	v_lshlrev_b32_e32 v68, 16, v220
	v_and_b32_e32 v69, 0xffff0000, v220
	v_lshlrev_b32_e32 v70, 16, v221
	v_and_b32_e32 v71, 0xffff0000, v221
	v_lshlrev_b32_e32 v64, 16, v222
	v_and_b32_e32 v65, 0xffff0000, v222
	v_lshlrev_b32_e32 v66, 16, v223
	v_and_b32_e32 v67, 0xffff0000, v223
	v_lshlrev_b32_e32 v60, 16, v224
	v_and_b32_e32 v61, 0xffff0000, v224
	v_lshlrev_b32_e32 v62, 16, v225
	v_and_b32_e32 v63, 0xffff0000, v225
	v_lshlrev_b32_e32 v56, 16, v226
	v_and_b32_e32 v57, 0xffff0000, v226
	v_lshlrev_b32_e32 v58, 16, v227
	v_and_b32_e32 v59, 0xffff0000, v227
	v_lshlrev_b32_e32 v52, 16, v228
	v_and_b32_e32 v53, 0xffff0000, v228
	v_lshlrev_b32_e32 v54, 16, v229
	v_and_b32_e32 v55, 0xffff0000, v229
	v_lshlrev_b32_e32 v48, 16, v230
	v_and_b32_e32 v49, 0xffff0000, v230
	v_lshlrev_b32_e32 v50, 16, v231
	v_and_b32_e32 v51, 0xffff0000, v231
	v_lshlrev_b32_e32 v44, 16, v232
	v_and_b32_e32 v45, 0xffff0000, v232
	v_lshlrev_b32_e32 v46, 16, v233
	v_and_b32_e32 v47, 0xffff0000, v233
	v_lshlrev_b32_e32 v40, 16, v234
	v_and_b32_e32 v41, 0xffff0000, v234
	v_lshlrev_b32_e32 v42, 16, v235
	v_and_b32_e32 v43, 0xffff0000, v235
	v_lshlrev_b32_e32 v36, 16, v236
	v_and_b32_e32 v37, 0xffff0000, v236
	v_lshlrev_b32_e32 v38, 16, v237
	v_and_b32_e32 v39, 0xffff0000, v237
	v_lshlrev_b32_e32 v32, 16, v238
	v_and_b32_e32 v33, 0xffff0000, v238
	v_lshlrev_b32_e32 v34, 16, v239
	v_and_b32_e32 v35, 0xffff0000, v239
	v_lshlrev_b32_e32 v28, 16, v240
	v_and_b32_e32 v29, 0xffff0000, v240
	v_lshlrev_b32_e32 v30, 16, v241
	v_and_b32_e32 v31, 0xffff0000, v241
	v_lshlrev_b32_e32 v24, 16, v242
	v_and_b32_e32 v25, 0xffff0000, v242
	v_lshlrev_b32_e32 v26, 16, v243
	v_and_b32_e32 v27, 0xffff0000, v243
	v_lshlrev_b32_e32 v20, 16, v244
	v_and_b32_e32 v21, 0xffff0000, v244
	v_lshlrev_b32_e32 v22, 16, v245
	v_and_b32_e32 v23, 0xffff0000, v245
	v_lshlrev_b32_e32 v16, 16, v246
	v_and_b32_e32 v17, 0xffff0000, v246
	v_lshlrev_b32_e32 v18, 16, v247
	v_and_b32_e32 v19, 0xffff0000, v247
	v_lshlrev_b32_e32 v12, 16, v248
	v_and_b32_e32 v13, 0xffff0000, v248
	v_lshlrev_b32_e32 v14, 16, v249
	v_and_b32_e32 v15, 0xffff0000, v249
	v_lshlrev_b32_e32 v8, 16, v250
	v_and_b32_e32 v9, 0xffff0000, v250
	v_lshlrev_b32_e32 v10, 16, v251
	v_and_b32_e32 v11, 0xffff0000, v251
	v_lshlrev_b32_e32 v4, 16, v252
	v_and_b32_e32 v5, 0xffff0000, v252
	v_lshlrev_b32_e32 v6, 16, v253
	v_and_b32_e32 v7, 0xffff0000, v253
	s_barrier
	s_branch .LBB0_1364

.LBB0_1376:
	s_lshl_b32 s18, s8, 8
	s_add_i32 s2, s18, s62
	v_or_b32_e32 v166, s2, v3
	s_lshl_b32 s2, s0, 8
	s_lshl_b32 s3, s9, 6
	s_or_b32 s2, s2, s3
	v_ashrrev_i32_e32 v167, 31, v166
	v_lshl_or_b32 v0, v142, 3, s2
	v_cmp_gt_u32_e64 s[2:3], 8, v3
	v_mov_b32_e32 v3, 0xffffc040
	v_lshlrev_b64 v[132:133], 11, v[166:167]
	v_ashrrev_i32_e32 v1, 31, v0
	v_cndmask_b32_e64 v162, v3, 0, s[2:3]
	v_mov_b32_e32 v3, 0x4040
	v_lshl_add_u64 v[132:133], s[42:43], 0, v[132:133]
	v_cndmask_b32_e64 v163, -1, 0, s[2:3]
	v_cndmask_b32_e64 v164, 0, v3, s[2:3]
	v_mov_b32_e32 v165, 0
	v_lshl_add_u64 v[132:133], v[0:1], 1, v[132:133]
	v_lshl_add_u64 v[134:135], v[132:133], 0, v[162:163]
	v_lshl_add_u64 v[136:137], v[132:133], 0, v[164:165]
	s_barrier
	s_nop 0
	v_mbcnt_lo_u32_b32 v3, -1, 0
	v_mbcnt_hi_u32_b32 v3, -1, v3
	v_and_b32_e32 v145, 64, v3
	v_xor_b32_e32 v144, 16, v3
	v_add_u32_e32 v170, 64, v145
	v_cmp_lt_i32_e32 vcc, v144, v170
	v_mov_b32_e32 v140, v165
	v_mov_b32_e32 v141, v165
	v_cndmask_b32_e32 v144, v3, v144, vcc
	v_lshlrev_b32_e32 v169, 2, v144
	v_mov_b32_e32 v142, v165
	v_mov_b32_e32 v143, v165
	s_lshl_b32 s4, s9, 2
	s_add_i32 s6, s4, 0x100
	s_waitcnt vmcnt(0)
	v_cndmask_b32_e64 v144, v136, v132, s[2:3]
	v_cndmask_b32_e64 v145, v137, v133, s[2:3]
	v_cndmask_b32_e64 v146, v138, v134, s[2:3]
	v_cndmask_b32_e64 v147, v139, v135, s[2:3]
	v_cndmask_b32_e64 v132, v132, v136, s[2:3]
	v_cndmask_b32_e64 v133, v133, v137, s[2:3]
	v_cndmask_b32_e64 v134, v134, v138, s[2:3]
	v_cndmask_b32_e64 v135, v135, v139, s[2:3]
	v_mov_b32_dpp v140, v132 row_ror:8 row_mask:0xf bank_mask:0xf
	v_mov_b32_dpp v141, v133 row_ror:8 row_mask:0xf bank_mask:0xf
	v_lshlrev_b32_e32 v136, 16, v146
	v_and_b32_e32 v137, 0xffff0000, v146
	v_lshlrev_b32_e32 v138, 16, v147
	v_and_b32_e32 v139, 0xffff0000, v147
	v_mov_b32_dpp v142, v134 row_ror:8 row_mask:0xf bank_mask:0xf
	v_mov_b32_dpp v143, v135 row_ror:8 row_mask:0xf bank_mask:0xf
	v_lshlrev_b32_e32 v132, 16, v144
	v_and_b32_e32 v133, 0xffff0000, v144
	v_lshlrev_b32_e32 v134, 16, v145
	v_and_b32_e32 v135, 0xffff0000, v145
	v_pk_mov_b32 v[152:153], v[126:127], v[126:127] op_sel:[0,1]
	v_pk_mov_b32 v[154:155], v[124:125], v[124:125] op_sel:[0,1]
	v_lshlrev_b32_e32 v124, 16, v140
	v_and_b32_e32 v125, 0xffff0000, v140
	v_lshlrev_b32_e32 v126, 16, v141
	v_and_b32_e32 v127, 0xffff0000, v141
	v_pk_mov_b32 v[158:159], v[130:131], v[130:131] op_sel:[0,1]
	v_pk_mov_b32 v[160:161], v[128:129], v[128:129] op_sel:[0,1]
	v_lshlrev_b32_e32 v128, 16, v142
	v_and_b32_e32 v129, 0xffff0000, v142
	v_pk_mov_b32 v[148:149], v[122:123], v[122:123] op_sel:[0,1]
	v_pk_mov_b32 v[150:151], v[120:121], v[120:121] op_sel:[0,1]
	v_lshlrev_b32_e32 v130, 16, v143
	v_and_b32_e32 v131, 0xffff0000, v143
	v_mul_f32_e32 v132, v161, v161
	v_mul_f32_e32 v133, v159, v159
	v_pk_mov_b32 v[146:147], v[116:117], v[116:117] op_sel:[0,1]
	v_mul_f32_e32 v116, v151, v151
	v_mul_f32_e32 v117, v149, v149
	v_mul_f32_e32 v134, v155, v155
	v_pk_mov_b32 v[144:145], v[118:119], v[118:119] op_sel:[0,1]
	v_fmac_f32_e32 v132, v160, v160
	v_fmac_f32_e32 v133, v158, v158
	v_mul_f32_e32 v118, v147, v147
	v_fmac_f32_e32 v116, v150, v150
	v_fmac_f32_e32 v117, v148, v148
	v_mul_f32_e32 v135, v153, v153
	v_fmac_f32_e32 v134, v154, v154
	v_mul_f32_e32 v119, v145, v145
	v_add_f32_e32 v120, v132, v133
	v_fmac_f32_e32 v118, v146, v146
	v_add_f32_e32 v116, v116, v117
	v_fmac_f32_e32 v135, v152, v152
	v_add_f32_e32 v120, v134, v120
	v_add_f32_e32 v116, v116, v118
	v_fmac_f32_e32 v119, v144, v144
	v_add_f32_e32 v117, v135, v120
	v_add_f32_e32 v116, v119, v116
	v_add_f32_e32 v116, v116, v117
	ds_bpermute_b32 v117, v169, v116
	v_xor_b32_e32 v118, 32, v3
	v_cmp_lt_i32_e32 vcc, v118, v170
	v_lshl_add_u32 v170, v168, 4, s6
	s_nop 0
	v_cndmask_b32_e32 v3, v3, v118, vcc
	v_lshlrev_b32_e32 v171, 2, v3
	s_waitcnt lgkmcnt(0)
	v_add_f32_e32 v3, v116, v117
	ds_bpermute_b32 v116, v171, v3
	v_cmp_gt_u32_e32 vcc, 16, v157
	s_and_saveexec_b64 s[4:5], vcc
	v_readlane_b32 s22, v254, 13
	v_readlane_b32 s23, v254, 14
	s_cbranch_execz .LBB0_1378
	s_waitcnt lgkmcnt(0)
	v_add_f32_e32 v3, v3, v116
	ds_write_b32 v170, v3
.LBB0_1378:
	s_or_b64 exec, exec, s[4:5]
	s_waitcnt lgkmcnt(0)
	v_or_b32_e32 v116, 16, v166
	v_ashrrev_i32_e32 v117, 31, v116
	v_lshlrev_b64 v[116:117], 11, v[116:117]
	v_lshl_add_u64 v[116:117], s[42:43], 0, v[116:117]
	v_lshl_add_u64 v[116:117], v[0:1], 1, v[116:117]
	v_lshl_add_u64 v[118:119], v[116:117], 0, v[162:163]
	v_lshl_add_u64 v[120:121], v[116:117], 0, v[164:165]
	s_nop 0
	v_mov_b32_e32 v3, v165
	v_mov_b32_e32 v124, v165
	v_mov_b32_e32 v125, v165
	v_mov_b32_e32 v126, v165
	s_waitcnt vmcnt(0)
	v_cndmask_b32_e64 v127, v120, v116, s[2:3]
	v_cndmask_b32_e64 v128, v121, v117, s[2:3]
	v_cndmask_b32_e64 v129, v122, v118, s[2:3]
	v_cndmask_b32_e64 v130, v123, v119, s[2:3]
	v_cndmask_b32_e64 v116, v116, v120, s[2:3]
	v_cndmask_b32_e64 v117, v117, v121, s[2:3]
	v_cndmask_b32_e64 v118, v118, v122, s[2:3]
	v_cndmask_b32_e64 v119, v119, v123, s[2:3]
	v_mov_b32_dpp v3, v116 row_ror:8 row_mask:0xf bank_mask:0xf
	v_mov_b32_dpp v124, v117 row_ror:8 row_mask:0xf bank_mask:0xf
	v_lshlrev_b32_e32 v120, 16, v129
	v_and_b32_e32 v121, 0xffff0000, v129
	v_lshlrev_b32_e32 v122, 16, v130
	v_and_b32_e32 v123, 0xffff0000, v130
	v_mov_b32_dpp v125, v118 row_ror:8 row_mask:0xf bank_mask:0xf
	v_mov_b32_dpp v126, v119 row_ror:8 row_mask:0xf bank_mask:0xf
	v_lshlrev_b32_e32 v116, 16, v127
	v_and_b32_e32 v117, 0xffff0000, v127
	v_lshlrev_b32_e32 v118, 16, v128
	v_and_b32_e32 v119, 0xffff0000, v128
	v_pk_mov_b32 v[136:137], v[110:111], v[110:111] op_sel:[0,1]
	v_pk_mov_b32 v[138:139], v[108:109], v[108:109] op_sel:[0,1]
	v_lshlrev_b32_e32 v108, 16, v3
	v_and_b32_e32 v109, 0xffff0000, v3
	v_lshlrev_b32_e32 v110, 16, v124
	v_and_b32_e32 v111, 0xffff0000, v124
	v_pk_mov_b32 v[140:141], v[114:115], v[114:115] op_sel:[0,1]
	v_pk_mov_b32 v[142:143], v[112:113], v[112:113] op_sel:[0,1]
	v_lshlrev_b32_e32 v112, 16, v125
	v_and_b32_e32 v113, 0xffff0000, v125
	v_pk_mov_b32 v[132:133], v[106:107], v[106:107] op_sel:[0,1]
	v_pk_mov_b32 v[134:135], v[104:105], v[104:105] op_sel:[0,1]
	v_lshlrev_b32_e32 v114, 16, v126
	v_and_b32_e32 v115, 0xffff0000, v126
	v_mul_f32_e32 v3, v143, v143
	v_mul_f32_e32 v116, v141, v141
	v_pk_mov_b32 v[130:131], v[100:101], v[100:101] op_sel:[0,1]
	v_mul_f32_e32 v100, v135, v135
	v_mul_f32_e32 v101, v133, v133
	v_mul_f32_e32 v117, v139, v139
	v_pk_mov_b32 v[126:127], v[102:103], v[102:103] op_sel:[0,1]
	v_fmac_f32_e32 v3, v142, v142
	v_fmac_f32_e32 v116, v140, v140
	v_mul_f32_e32 v102, v131, v131
	v_fmac_f32_e32 v100, v134, v134
	v_fmac_f32_e32 v101, v132, v132
	v_mul_f32_e32 v118, v137, v137
	v_fmac_f32_e32 v117, v138, v138
	v_mul_f32_e32 v103, v127, v127
	v_add_f32_e32 v3, v3, v116
	v_fmac_f32_e32 v102, v130, v130
	v_add_f32_e32 v100, v100, v101
	v_fmac_f32_e32 v118, v136, v136
	v_add_f32_e32 v3, v117, v3
	v_add_f32_e32 v100, v100, v102
	v_fmac_f32_e32 v103, v126, v126
	v_add_f32_e32 v3, v118, v3
	v_add_f32_e32 v100, v103, v100
	v_add_f32_e32 v3, v100, v3
	ds_bpermute_b32 v100, v169, v3
	s_waitcnt lgkmcnt(0)
	v_add_f32_e32 v3, v3, v100
	ds_bpermute_b32 v100, v171, v3
	s_and_saveexec_b64 s[4:5], vcc
	s_cbranch_execz .LBB0_1380
	s_waitcnt lgkmcnt(0)
	v_add_f32_e32 v3, v3, v100
	ds_write_b32 v170, v3 offset:256
.LBB0_1380:
	s_or_b64 exec, exec, s[4:5]
	s_waitcnt lgkmcnt(0)
	v_or_b32_e32 v100, 32, v166
	v_ashrrev_i32_e32 v101, 31, v100
	v_lshlrev_b64 v[100:101], 11, v[100:101]
	v_lshl_add_u64 v[100:101], s[42:43], 0, v[100:101]
	v_lshl_add_u64 v[100:101], v[0:1], 1, v[100:101]
	v_lshl_add_u64 v[102:103], v[100:101], 0, v[162:163]
	v_lshl_add_u64 v[104:105], v[100:101], 0, v[164:165]
	s_nop 0
	v_mov_b32_e32 v3, 0
	v_mov_b32_e32 v108, 0
	v_mov_b32_e32 v109, 0
	v_mov_b32_e32 v110, 0
	s_waitcnt vmcnt(0)
	v_cndmask_b32_e64 v111, v104, v100, s[2:3]
	v_cndmask_b32_e64 v112, v105, v101, s[2:3]
	v_cndmask_b32_e64 v113, v106, v102, s[2:3]
	v_cndmask_b32_e64 v114, v107, v103, s[2:3]
	v_cndmask_b32_e64 v100, v100, v104, s[2:3]
	v_cndmask_b32_e64 v101, v101, v105, s[2:3]
	v_cndmask_b32_e64 v102, v102, v106, s[2:3]
	v_cndmask_b32_e64 v103, v103, v107, s[2:3]
	v_mov_b32_dpp v3, v100 row_ror:8 row_mask:0xf bank_mask:0xf
	v_mov_b32_dpp v108, v101 row_ror:8 row_mask:0xf bank_mask:0xf
	v_lshlrev_b32_e32 v104, 16, v113
	v_and_b32_e32 v105, 0xffff0000, v113
	v_lshlrev_b32_e32 v106, 16, v114
	v_and_b32_e32 v107, 0xffff0000, v114
	v_mov_b32_dpp v109, v102 row_ror:8 row_mask:0xf bank_mask:0xf
	v_mov_b32_dpp v110, v103 row_ror:8 row_mask:0xf bank_mask:0xf
	v_lshlrev_b32_e32 v100, 16, v111
	v_and_b32_e32 v101, 0xffff0000, v111
	v_lshlrev_b32_e32 v102, 16, v112
	v_and_b32_e32 v103, 0xffff0000, v112
	v_pk_mov_b32 v[120:121], v[94:95], v[94:95] op_sel:[0,1]
	v_pk_mov_b32 v[122:123], v[92:93], v[92:93] op_sel:[0,1]
	v_lshlrev_b32_e32 v92, 16, v3
	v_and_b32_e32 v93, 0xffff0000, v3
	v_lshlrev_b32_e32 v94, 16, v108
	v_and_b32_e32 v95, 0xffff0000, v108
	v_pk_mov_b32 v[124:125], v[98:99], v[98:99] op_sel:[0,1]
	v_pk_mov_b32 v[128:129], v[96:97], v[96:97] op_sel:[0,1]
	v_lshlrev_b32_e32 v96, 16, v109
	v_and_b32_e32 v97, 0xffff0000, v109
	v_pk_mov_b32 v[116:117], v[90:91], v[90:91] op_sel:[0,1]
	v_pk_mov_b32 v[118:119], v[88:89], v[88:89] op_sel:[0,1]
	v_lshlrev_b32_e32 v98, 16, v110
	v_and_b32_e32 v99, 0xffff0000, v110
	v_mul_f32_e32 v3, v129, v129
	v_mul_f32_e32 v100, v125, v125
	v_pk_mov_b32 v[114:115], v[84:85], v[84:85] op_sel:[0,1]
	v_mul_f32_e32 v84, v119, v119
	v_mul_f32_e32 v85, v117, v117
	v_mul_f32_e32 v101, v123, v123
	v_pk_mov_b32 v[112:113], v[86:87], v[86:87] op_sel:[0,1]
	v_fmac_f32_e32 v3, v128, v128
	v_fmac_f32_e32 v100, v124, v124
	v_mul_f32_e32 v86, v115, v115
	v_fmac_f32_e32 v84, v118, v118
	v_fmac_f32_e32 v85, v116, v116
	v_mul_f32_e32 v102, v121, v121
	v_fmac_f32_e32 v101, v122, v122
	v_mul_f32_e32 v87, v113, v113
	v_add_f32_e32 v3, v3, v100
	v_fmac_f32_e32 v86, v114, v114
	v_add_f32_e32 v84, v84, v85
	v_fmac_f32_e32 v102, v120, v120
	v_add_f32_e32 v3, v101, v3
	v_add_f32_e32 v84, v84, v86
	v_fmac_f32_e32 v87, v112, v112
	v_add_f32_e32 v3, v102, v3
	v_add_f32_e32 v84, v87, v84
	v_add_f32_e32 v3, v84, v3
	ds_bpermute_b32 v84, v169, v3
	s_waitcnt lgkmcnt(0)
	v_add_f32_e32 v84, v3, v84
	ds_bpermute_b32 v85, v171, v84
	v_mov_b32_e32 v3, 0
	s_and_saveexec_b64 s[4:5], vcc
	s_cbranch_execz .LBB0_1382
	s_waitcnt lgkmcnt(0)
	v_add_f32_e32 v84, v84, v85
	ds_write_b32 v170, v84 offset:512
.LBB0_1382:
	s_or_b64 exec, exec, s[4:5]
	v_or_b32_e32 v84, 48, v166
	s_waitcnt lgkmcnt(0)
	v_ashrrev_i32_e32 v85, 31, v84
	v_lshlrev_b64 v[84:85], 11, v[84:85]
	v_lshl_add_u64 v[84:85], s[42:43], 0, v[84:85]
	v_lshl_add_u64 v[84:85], v[0:1], 1, v[84:85]
	v_lshl_add_u64 v[86:87], v[84:85], 0, v[162:163]
	v_lshl_add_u64 v[88:89], v[84:85], 0, v[164:165]
	s_nop 0
	v_mov_b32_e32 v92, 0
	v_mov_b32_e32 v93, 0
	v_mov_b32_e32 v94, 0
	s_waitcnt vmcnt(0)
	v_cndmask_b32_e64 v95, v88, v84, s[2:3]
	v_cndmask_b32_e64 v96, v89, v85, s[2:3]
	v_cndmask_b32_e64 v97, v90, v86, s[2:3]
	v_cndmask_b32_e64 v98, v91, v87, s[2:3]
	v_cndmask_b32_e64 v84, v84, v88, s[2:3]
	v_cndmask_b32_e64 v85, v85, v89, s[2:3]
	v_cndmask_b32_e64 v86, v86, v90, s[2:3]
	v_cndmask_b32_e64 v87, v87, v91, s[2:3]
	v_mov_b32_dpp v92, v84 row_ror:8 row_mask:0xf bank_mask:0xf
	v_mov_b32_dpp v93, v85 row_ror:8 row_mask:0xf bank_mask:0xf
	v_lshlrev_b32_e32 v88, 16, v97
	v_and_b32_e32 v89, 0xffff0000, v97
	v_lshlrev_b32_e32 v90, 16, v98
	v_and_b32_e32 v91, 0xffff0000, v98
	v_mov_b32_dpp v94, v86 row_ror:8 row_mask:0xf bank_mask:0xf
	v_mov_b32_dpp v3, v87 row_ror:8 row_mask:0xf bank_mask:0xf
	v_lshlrev_b32_e32 v84, 16, v95
	v_and_b32_e32 v85, 0xffff0000, v95
	v_lshlrev_b32_e32 v86, 16, v96
	v_and_b32_e32 v87, 0xffff0000, v96
	v_pk_mov_b32 v[104:105], v[78:79], v[78:79] op_sel:[0,1]
	v_pk_mov_b32 v[106:107], v[76:77], v[76:77] op_sel:[0,1]
	v_lshlrev_b32_e32 v76, 16, v92
	v_and_b32_e32 v77, 0xffff0000, v92
	v_lshlrev_b32_e32 v78, 16, v93
	v_and_b32_e32 v79, 0xffff0000, v93
	v_pk_mov_b32 v[108:109], v[82:83], v[82:83] op_sel:[0,1]
	v_pk_mov_b32 v[110:111], v[80:81], v[80:81] op_sel:[0,1]
	v_lshlrev_b32_e32 v80, 16, v94
	v_and_b32_e32 v81, 0xffff0000, v94
	v_pk_mov_b32 v[100:101], v[74:75], v[74:75] op_sel:[0,1]
	v_pk_mov_b32 v[102:103], v[72:73], v[72:73] op_sel:[0,1]
	v_lshlrev_b32_e32 v82, 16, v3
	v_and_b32_e32 v83, 0xffff0000, v3
	v_mul_f32_e32 v3, v111, v111
	v_mul_f32_e32 v84, v109, v109
	v_pk_mov_b32 v[98:99], v[68:69], v[68:69] op_sel:[0,1]
	v_mul_f32_e32 v68, v103, v103
	v_mul_f32_e32 v69, v101, v101
	v_mul_f32_e32 v85, v107, v107
	v_pk_mov_b32 v[94:95], v[70:71], v[70:71] op_sel:[0,1]
	v_fmac_f32_e32 v3, v110, v110
	v_fmac_f32_e32 v84, v108, v108
	v_mul_f32_e32 v70, v99, v99
	v_fmac_f32_e32 v68, v102, v102
	v_fmac_f32_e32 v69, v100, v100
	v_mul_f32_e32 v86, v105, v105
	v_fmac_f32_e32 v85, v106, v106
	v_mul_f32_e32 v71, v95, v95
	v_add_f32_e32 v3, v3, v84
	v_fmac_f32_e32 v70, v98, v98
	v_add_f32_e32 v68, v68, v69
	v_fmac_f32_e32 v86, v104, v104
	v_add_f32_e32 v3, v85, v3
	v_add_f32_e32 v68, v68, v70
	v_fmac_f32_e32 v71, v94, v94
	v_add_f32_e32 v3, v86, v3
	v_add_f32_e32 v68, v71, v68
	v_add_f32_e32 v3, v68, v3
	ds_bpermute_b32 v68, v169, v3
	s_waitcnt lgkmcnt(0)
	v_add_f32_e32 v3, v3, v68
	ds_bpermute_b32 v68, v171, v3
	s_and_saveexec_b64 s[4:5], vcc
	s_cbranch_execz .LBB0_1384
	s_waitcnt lgkmcnt(0)
	v_add_f32_e32 v3, v3, v68
	ds_write_b32 v170, v3 offset:768
.LBB0_1384:
	s_or_b64 exec, exec, s[4:5]
	s_waitcnt lgkmcnt(0)
	v_lshlrev_b64 v[68:69], 11, v[166:167]
	v_lshl_add_u64 v[68:69], s[42:43], 0, v[68:69]
	v_lshl_add_u64 v[68:69], v[0:1], 1, v[68:69]
	s_mov_b64 s[4:5], 0x40000
	v_lshl_add_u64 v[70:71], v[68:69], 0, s[4:5]
	v_lshl_add_u64 v[72:73], v[70:71], 0, v[162:163]
	v_lshl_add_u64 v[74:75], v[70:71], 0, v[164:165]
	s_nop 0
	v_mov_b32_e32 v3, 0
	v_mov_b32_e32 v78, 0
	v_mov_b32_e32 v79, 0
	v_mov_b32_e32 v80, 0
	s_waitcnt vmcnt(0)
	v_cndmask_b32_e64 v81, v74, v70, s[2:3]
	v_cndmask_b32_e64 v82, v75, v71, s[2:3]
	v_cndmask_b32_e64 v83, v76, v72, s[2:3]
	v_cndmask_b32_e64 v84, v77, v73, s[2:3]
	v_cndmask_b32_e64 v70, v70, v74, s[2:3]
	v_cndmask_b32_e64 v71, v71, v75, s[2:3]
	v_cndmask_b32_e64 v72, v72, v76, s[2:3]
	v_cndmask_b32_e64 v73, v73, v77, s[2:3]
	v_mov_b32_dpp v3, v70 row_ror:8 row_mask:0xf bank_mask:0xf
	v_mov_b32_dpp v78, v71 row_ror:8 row_mask:0xf bank_mask:0xf
	v_lshlrev_b32_e32 v74, 16, v83
	v_and_b32_e32 v75, 0xffff0000, v83
	v_lshlrev_b32_e32 v76, 16, v84
	v_and_b32_e32 v77, 0xffff0000, v84
	v_mov_b32_dpp v79, v72 row_ror:8 row_mask:0xf bank_mask:0xf
	v_mov_b32_dpp v80, v73 row_ror:8 row_mask:0xf bank_mask:0xf
	v_lshlrev_b32_e32 v70, 16, v81
	v_and_b32_e32 v71, 0xffff0000, v81
	v_lshlrev_b32_e32 v72, 16, v82
	v_and_b32_e32 v73, 0xffff0000, v82
	v_pk_mov_b32 v[88:89], v[62:63], v[62:63] op_sel:[0,1]
	v_pk_mov_b32 v[90:91], v[60:61], v[60:61] op_sel:[0,1]
	v_lshlrev_b32_e32 v60, 16, v3
	v_and_b32_e32 v61, 0xffff0000, v3
	v_lshlrev_b32_e32 v62, 16, v78
	v_and_b32_e32 v63, 0xffff0000, v78
	v_pk_mov_b32 v[92:93], v[66:67], v[66:67] op_sel:[0,1]
	v_pk_mov_b32 v[96:97], v[64:65], v[64:65] op_sel:[0,1]
	v_lshlrev_b32_e32 v64, 16, v79
	v_and_b32_e32 v65, 0xffff0000, v79
	v_pk_mov_b32 v[84:85], v[58:59], v[58:59] op_sel:[0,1]
	v_pk_mov_b32 v[86:87], v[56:57], v[56:57] op_sel:[0,1]
	v_lshlrev_b32_e32 v66, 16, v80
	v_and_b32_e32 v67, 0xffff0000, v80
	v_mul_f32_e32 v3, v97, v97
	v_mul_f32_e32 v70, v93, v93
	v_pk_mov_b32 v[82:83], v[52:53], v[52:53] op_sel:[0,1]
	v_mul_f32_e32 v52, v87, v87
	v_mul_f32_e32 v53, v85, v85
	v_mul_f32_e32 v71, v91, v91
	v_pk_mov_b32 v[80:81], v[54:55], v[54:55] op_sel:[0,1]
	v_fmac_f32_e32 v3, v96, v96
	v_fmac_f32_e32 v70, v92, v92
	v_mul_f32_e32 v54, v83, v83
	v_fmac_f32_e32 v52, v86, v86
	v_fmac_f32_e32 v53, v84, v84
	v_mul_f32_e32 v72, v89, v89
	v_fmac_f32_e32 v71, v90, v90
	v_mul_f32_e32 v55, v81, v81
	v_add_f32_e32 v3, v3, v70
	v_fmac_f32_e32 v54, v82, v82
	v_add_f32_e32 v52, v52, v53
	v_fmac_f32_e32 v72, v88, v88
	v_add_f32_e32 v3, v71, v3
	v_add_f32_e32 v52, v52, v54
	v_fmac_f32_e32 v55, v80, v80
	v_add_f32_e32 v3, v72, v3
	v_add_f32_e32 v52, v55, v52
	v_add_f32_e32 v3, v52, v3
	ds_bpermute_b32 v52, v169, v3
	s_waitcnt lgkmcnt(0)
	v_add_f32_e32 v53, v3, v52
	ds_bpermute_b32 v54, v171, v53
	v_add_u32_e32 v3, 0x80, v168
	v_mov_b32_e32 v52, 0
	s_and_saveexec_b64 s[4:5], vcc
	s_cbranch_execz .LBB0_1386
	v_lshl_add_u32 v55, v3, 4, s6
	s_waitcnt lgkmcnt(0)
	v_add_f32_e32 v53, v53, v54
	ds_write_b32 v55, v53
.LBB0_1386:
	s_or_b64 exec, exec, s[4:5]
	s_mov_b64 s[4:5], 0x48000
	s_waitcnt lgkmcnt(0)
	v_lshl_add_u64 v[54:55], v[68:69], 0, s[4:5]
	v_lshl_add_u64 v[56:57], v[54:55], 0, v[162:163]
	v_lshl_add_u64 v[58:59], v[54:55], 0, v[164:165]
	s_nop 0
	v_mov_b32_e32 v53, 0
	v_mov_b32_e32 v62, 0
	v_mov_b32_e32 v63, 0
	s_waitcnt vmcnt(0)
	v_cndmask_b32_e64 v64, v58, v54, s[2:3]
	v_cndmask_b32_e64 v65, v59, v55, s[2:3]
	v_cndmask_b32_e64 v66, v60, v56, s[2:3]
	v_cndmask_b32_e64 v67, v61, v57, s[2:3]
	v_cndmask_b32_e64 v54, v54, v58, s[2:3]
	v_cndmask_b32_e64 v55, v55, v59, s[2:3]
	v_cndmask_b32_e64 v56, v56, v60, s[2:3]
	v_cndmask_b32_e64 v57, v57, v61, s[2:3]
	v_mov_b32_dpp v53, v54 row_ror:8 row_mask:0xf bank_mask:0xf
	v_mov_b32_dpp v62, v55 row_ror:8 row_mask:0xf bank_mask:0xf
	v_lshlrev_b32_e32 v58, 16, v66
	v_and_b32_e32 v59, 0xffff0000, v66
	v_lshlrev_b32_e32 v60, 16, v67
	v_and_b32_e32 v61, 0xffff0000, v67
	v_mov_b32_dpp v63, v56 row_ror:8 row_mask:0xf bank_mask:0xf
	v_mov_b32_dpp v52, v57 row_ror:8 row_mask:0xf bank_mask:0xf
	v_lshlrev_b32_e32 v54, 16, v64
	v_and_b32_e32 v55, 0xffff0000, v64
	v_lshlrev_b32_e32 v56, 16, v65
	v_and_b32_e32 v57, 0xffff0000, v65
	v_pk_mov_b32 v[72:73], v[46:47], v[46:47] op_sel:[0,1]
	v_pk_mov_b32 v[74:75], v[44:45], v[44:45] op_sel:[0,1]
	v_lshlrev_b32_e32 v44, 16, v53
	v_and_b32_e32 v45, 0xffff0000, v53
	v_lshlrev_b32_e32 v46, 16, v62
	v_and_b32_e32 v47, 0xffff0000, v62
	v_pk_mov_b32 v[76:77], v[50:51], v[50:51] op_sel:[0,1]
	v_pk_mov_b32 v[78:79], v[48:49], v[48:49] op_sel:[0,1]
	v_lshlrev_b32_e32 v48, 16, v63
	v_and_b32_e32 v49, 0xffff0000, v63
	v_pk_mov_b32 v[68:69], v[42:43], v[42:43] op_sel:[0,1]
	v_pk_mov_b32 v[70:71], v[40:41], v[40:41] op_sel:[0,1]
	v_lshlrev_b32_e32 v50, 16, v52
	v_and_b32_e32 v51, 0xffff0000, v52
	v_mul_f32_e32 v52, v79, v79
	v_mul_f32_e32 v53, v77, v77
	v_pk_mov_b32 v[66:67], v[36:37], v[36:37] op_sel:[0,1]
	v_mul_f32_e32 v36, v71, v71
	v_mul_f32_e32 v37, v69, v69
	v_mul_f32_e32 v54, v75, v75
	v_pk_mov_b32 v[62:63], v[38:39], v[38:39] op_sel:[0,1]
	v_fmac_f32_e32 v52, v78, v78
	v_fmac_f32_e32 v53, v76, v76
	v_mul_f32_e32 v38, v67, v67
	v_fmac_f32_e32 v36, v70, v70
	v_fmac_f32_e32 v37, v68, v68
	v_mul_f32_e32 v55, v73, v73
	v_fmac_f32_e32 v54, v74, v74
	v_mul_f32_e32 v39, v63, v63
	v_add_f32_e32 v40, v52, v53
	v_fmac_f32_e32 v38, v66, v66
	v_add_f32_e32 v36, v36, v37
	v_fmac_f32_e32 v55, v72, v72
	v_add_f32_e32 v40, v54, v40
	v_add_f32_e32 v36, v36, v38
	v_fmac_f32_e32 v39, v62, v62
	v_add_f32_e32 v37, v55, v40
	v_add_f32_e32 v36, v39, v36
	v_add_f32_e32 v36, v36, v37
	ds_bpermute_b32 v37, v169, v36
	s_waitcnt lgkmcnt(0)
	v_add_f32_e32 v36, v36, v37
	ds_bpermute_b32 v37, v171, v36
	s_and_saveexec_b64 s[4:5], vcc
	s_cbranch_execz .LBB0_1388
	s_waitcnt lgkmcnt(0)
	v_add_f32_e32 v36, v36, v37
	ds_write_b32 v170, v36 offset:2304
.LBB0_1388:
	s_or_b64 exec, exec, s[4:5]
	s_waitcnt lgkmcnt(0)
	v_lshlrev_b64 v[36:37], 11, v[166:167]
	v_lshl_add_u64 v[36:37], s[42:43], 0, v[36:37]
	v_lshl_add_u64 v[36:37], v[0:1], 1, v[36:37]
	s_mov_b64 s[4:5], 0x50000
	v_lshl_add_u64 v[38:39], v[36:37], 0, s[4:5]
	v_lshl_add_u64 v[40:41], v[38:39], 0, v[162:163]
	v_lshl_add_u64 v[42:43], v[38:39], 0, v[164:165]
	s_nop 0
	v_mov_b32_e32 v46, 0
	v_mov_b32_e32 v47, 0
	v_mov_b32_e32 v48, 0
	v_mov_b32_e32 v49, 0
	s_waitcnt vmcnt(0)
	v_cndmask_b32_e64 v50, v42, v38, s[2:3]
	v_cndmask_b32_e64 v51, v43, v39, s[2:3]
	v_cndmask_b32_e64 v52, v44, v40, s[2:3]
	v_cndmask_b32_e64 v53, v45, v41, s[2:3]
	v_cndmask_b32_e64 v38, v38, v42, s[2:3]
	v_cndmask_b32_e64 v39, v39, v43, s[2:3]
	v_cndmask_b32_e64 v40, v40, v44, s[2:3]
	v_cndmask_b32_e64 v41, v41, v45, s[2:3]
	v_mov_b32_dpp v46, v38 row_ror:8 row_mask:0xf bank_mask:0xf
	v_mov_b32_dpp v47, v39 row_ror:8 row_mask:0xf bank_mask:0xf
	v_lshlrev_b32_e32 v42, 16, v52
	v_and_b32_e32 v43, 0xffff0000, v52
	v_lshlrev_b32_e32 v44, 16, v53
	v_and_b32_e32 v45, 0xffff0000, v53
	v_mov_b32_dpp v48, v40 row_ror:8 row_mask:0xf bank_mask:0xf
	v_mov_b32_dpp v49, v41 row_ror:8 row_mask:0xf bank_mask:0xf
	v_lshlrev_b32_e32 v38, 16, v50
	v_and_b32_e32 v39, 0xffff0000, v50
	v_lshlrev_b32_e32 v40, 16, v51
	v_and_b32_e32 v41, 0xffff0000, v51
	v_pk_mov_b32 v[56:57], v[30:31], v[30:31] op_sel:[0,1]
	v_pk_mov_b32 v[58:59], v[28:29], v[28:29] op_sel:[0,1]
	v_lshlrev_b32_e32 v28, 16, v46
	v_and_b32_e32 v29, 0xffff0000, v46
	v_lshlrev_b32_e32 v30, 16, v47
	v_and_b32_e32 v31, 0xffff0000, v47
	v_pk_mov_b32 v[60:61], v[34:35], v[34:35] op_sel:[0,1]
	v_pk_mov_b32 v[64:65], v[32:33], v[32:33] op_sel:[0,1]
	v_lshlrev_b32_e32 v32, 16, v48
	v_and_b32_e32 v33, 0xffff0000, v48
	v_pk_mov_b32 v[52:53], v[26:27], v[26:27] op_sel:[0,1]
	v_pk_mov_b32 v[54:55], v[24:25], v[24:25] op_sel:[0,1]
	v_lshlrev_b32_e32 v34, 16, v49
	v_and_b32_e32 v35, 0xffff0000, v49
	v_mul_f32_e32 v38, v65, v65
	v_mul_f32_e32 v39, v61, v61
	v_pk_mov_b32 v[50:51], v[20:21], v[20:21] op_sel:[0,1]
	v_mul_f32_e32 v20, v55, v55
	v_mul_f32_e32 v21, v53, v53
	v_mul_f32_e32 v40, v59, v59
	v_pk_mov_b32 v[48:49], v[22:23], v[22:23] op_sel:[0,1]
	v_fmac_f32_e32 v38, v64, v64
	v_fmac_f32_e32 v39, v60, v60
	v_mul_f32_e32 v22, v51, v51
	v_fmac_f32_e32 v20, v54, v54
	v_fmac_f32_e32 v21, v52, v52
	v_mul_f32_e32 v41, v57, v57
	v_fmac_f32_e32 v40, v58, v58
	v_mul_f32_e32 v23, v49, v49
	v_add_f32_e32 v24, v38, v39
	v_fmac_f32_e32 v22, v50, v50
	v_add_f32_e32 v20, v20, v21
	v_fmac_f32_e32 v41, v56, v56
	v_add_f32_e32 v24, v40, v24
	v_add_f32_e32 v20, v20, v22
	v_fmac_f32_e32 v23, v48, v48
	v_add_f32_e32 v21, v41, v24
	v_add_f32_e32 v20, v23, v20
	v_add_f32_e32 v20, v20, v21
	ds_bpermute_b32 v21, v169, v20
	s_waitcnt lgkmcnt(0)
	v_add_f32_e32 v21, v20, v21
	ds_bpermute_b32 v22, v171, v21
	v_mov_b32_e32 v20, 0
	s_and_saveexec_b64 s[4:5], vcc
	s_cbranch_execz .LBB0_1390
	s_waitcnt lgkmcnt(0)
	v_add_f32_e32 v21, v21, v22
	ds_write_b32 v170, v21 offset:2560
.LBB0_1390:
	s_or_b64 exec, exec, s[4:5]
	s_mov_b64 s[4:5], 0x58000
	s_waitcnt lgkmcnt(0)
	v_lshl_add_u64 v[22:23], v[36:37], 0, s[4:5]
	v_lshl_add_u64 v[24:25], v[22:23], 0, v[162:163]
	v_lshl_add_u64 v[26:27], v[22:23], 0, v[164:165]
	s_nop 0
	v_mov_b32_e32 v21, 0
	v_mov_b32_e32 v30, 0
	v_mov_b32_e32 v31, 0
	s_waitcnt vmcnt(0)
	v_cndmask_b32_e64 v32, v26, v22, s[2:3]
	v_cndmask_b32_e64 v33, v27, v23, s[2:3]
	v_cndmask_b32_e64 v34, v28, v24, s[2:3]
	v_cndmask_b32_e64 v35, v29, v25, s[2:3]
	v_cndmask_b32_e64 v22, v22, v26, s[2:3]
	v_cndmask_b32_e64 v23, v23, v27, s[2:3]
	v_cndmask_b32_e64 v24, v24, v28, s[2:3]
	v_cndmask_b32_e64 v25, v25, v29, s[2:3]
	v_mov_b32_dpp v21, v22 row_ror:8 row_mask:0xf bank_mask:0xf
	v_mov_b32_dpp v30, v23 row_ror:8 row_mask:0xf bank_mask:0xf
	v_lshlrev_b32_e32 v26, 16, v34
	v_and_b32_e32 v27, 0xffff0000, v34
	v_lshlrev_b32_e32 v28, 16, v35
	v_and_b32_e32 v29, 0xffff0000, v35
	v_mov_b32_dpp v31, v24 row_ror:8 row_mask:0xf bank_mask:0xf
	v_mov_b32_dpp v20, v25 row_ror:8 row_mask:0xf bank_mask:0xf
	v_lshlrev_b32_e32 v22, 16, v32
	v_and_b32_e32 v23, 0xffff0000, v32
	v_lshlrev_b32_e32 v24, 16, v33
	v_and_b32_e32 v25, 0xffff0000, v33
	v_pk_mov_b32 v[40:41], v[14:15], v[14:15] op_sel:[0,1]
	v_pk_mov_b32 v[42:43], v[12:13], v[12:13] op_sel:[0,1]
	v_lshlrev_b32_e32 v12, 16, v21
	v_and_b32_e32 v13, 0xffff0000, v21
	v_lshlrev_b32_e32 v14, 16, v30
	v_and_b32_e32 v15, 0xffff0000, v30
	v_pk_mov_b32 v[44:45], v[18:19], v[18:19] op_sel:[0,1]
	v_pk_mov_b32 v[46:47], v[16:17], v[16:17] op_sel:[0,1]
	v_lshlrev_b32_e32 v16, 16, v31
	v_and_b32_e32 v17, 0xffff0000, v31
	v_pk_mov_b32 v[36:37], v[10:11], v[10:11] op_sel:[0,1]
	v_pk_mov_b32 v[38:39], v[8:9], v[8:9] op_sel:[0,1]
	v_lshlrev_b32_e32 v18, 16, v20
	v_and_b32_e32 v19, 0xffff0000, v20
	v_mul_f32_e32 v20, v47, v47
	v_mul_f32_e32 v21, v45, v45
	v_pk_mov_b32 v[34:35], v[4:5], v[4:5] op_sel:[0,1]
	v_mul_f32_e32 v4, v39, v39
	v_mul_f32_e32 v5, v37, v37
	v_mul_f32_e32 v22, v43, v43
	v_pk_mov_b32 v[32:33], v[6:7], v[6:7] op_sel:[0,1]
	v_fmac_f32_e32 v20, v46, v46
	v_fmac_f32_e32 v21, v44, v44
	v_mul_f32_e32 v6, v35, v35
	v_fmac_f32_e32 v4, v38, v38
	v_fmac_f32_e32 v5, v36, v36
	v_mul_f32_e32 v23, v41, v41
	v_fmac_f32_e32 v22, v42, v42
	v_mul_f32_e32 v7, v33, v33
	v_add_f32_e32 v8, v20, v21
	v_fmac_f32_e32 v6, v34, v34
	v_add_f32_e32 v4, v4, v5
	v_fmac_f32_e32 v23, v40, v40
	v_add_f32_e32 v8, v22, v8
	v_add_f32_e32 v4, v4, v6
	v_fmac_f32_e32 v7, v32, v32
	v_add_f32_e32 v5, v23, v8
	v_add_f32_e32 v4, v7, v4
	v_add_f32_e32 v4, v4, v5
	ds_bpermute_b32 v5, v169, v4
	s_waitcnt lgkmcnt(0)
	v_add_f32_e32 v4, v4, v5
	ds_bpermute_b32 v5, v171, v4
	s_and_saveexec_b64 s[4:5], vcc
	s_cbranch_execz .LBB0_1392
	s_waitcnt lgkmcnt(0)
	v_add_f32_e32 v4, v4, v5
	ds_write_b32 v170, v4 offset:2816
